# v118: fused out-proj rounds visit row panels in reversed order (128-191 first)
# speedup vs baseline: 1.0038x; 1.0007x over previous
.LBB0_372:
	s_or_b64 exec, exec, s[2:3]
	s_cmpk_gt_i32 s75, 0x2ff
	s_waitcnt lgkmcnt(0)
	s_barrier
	s_cbranch_scc1 .LBB0_377
	s_mov_b32 s78, 0
	v_readlane_b32 s64, v254, 9
	s_cmpk_lg_i32 s64, 0x100
	s_cbranch_scc1 .Lp45_nofuse
	s_add_u32 s66, s42, 0x60d3c00
	s_addc_u32 s67, s43, 0
	v_mov_b32_e32 v20, 0
	global_load_dwordx4 v[24:27], v20, s[66:67] sc1
	global_load_dwordx4 v[28:31], v20, s[66:67] offset:16 sc1
	s_waitcnt vmcnt(0)
	v_readfirstlane_b32 s64, v24
	s_bcnt1_i32_b32 s64, s64
	s_cmp_lg_u32 s64, 1
	s_cbranch_scc1 .Lp45_nofuse
	v_readfirstlane_b32 s64, v25
	s_bcnt1_i32_b32 s64, s64
	s_cmp_lg_u32 s64, 1
	s_cbranch_scc1 .Lp45_nofuse
	v_readfirstlane_b32 s64, v26
	s_bcnt1_i32_b32 s64, s64
	s_cmp_lg_u32 s64, 1
	s_cbranch_scc1 .Lp45_nofuse
	v_readfirstlane_b32 s64, v27
	s_bcnt1_i32_b32 s64, s64
	s_cmp_lg_u32 s64, 1
	s_cbranch_scc1 .Lp45_nofuse
	v_readfirstlane_b32 s64, v28
	s_bcnt1_i32_b32 s64, s64
	s_cmp_lg_u32 s64, 1
	s_cbranch_scc1 .Lp45_nofuse
	v_readfirstlane_b32 s64, v29
	s_bcnt1_i32_b32 s64, s64
	s_cmp_lg_u32 s64, 1
	s_cbranch_scc1 .Lp45_nofuse
	v_readfirstlane_b32 s64, v30
	s_bcnt1_i32_b32 s64, s64
	s_cmp_lg_u32 s64, 1
	s_cbranch_scc1 .Lp45_nofuse
	v_readfirstlane_b32 s64, v31
	s_bcnt1_i32_b32 s64, s64
	s_cmp_lg_u32 s64, 1
	s_cbranch_scc1 .Lp45_nofuse
	s_mov_b32 s78, 1
	s_add_u32 s80, s42, 0x60d3800
	s_addc_u32 s81, s43, 0
	s_bfe_u32 s79, s75, 0x10002
	s_mov_b32 s82, 0
	s_mov_b32 s83, 0
	s_mov_b32 s84, s75
	s_add_i32 s75, s75, 0x200

.Lp45_loop:
	s_cmp_ge_u32 s83, s86
	s_cbranch_scc1 .Lp45_skip
	s_lshr_b32 s64, s84, 2
	s_movk_i32 s65, 0x0
	s_cmp_eq_u32 s83, 0
	s_cselect_b32 s65, 0x80, s65
	s_cmp_eq_u32 s83, 1
	s_cselect_b32 s65, 0x40, s65
	s_add_i32 s64, s64, s65
	s_cmp_lg_u32 s74, 0
	s_cbranch_scc1 .Lp45_ready
	s_lshl_b32 s65, s64, 2
	v_mov_b32_e32 v122, s65
	s_mov_b32 s67, 0

.Lp45_skip:
	s_cmp_eq_u32 s78, 0
	s_cbranch_scc1 .Lp45_oldctl
	s_movk_i32 s68, 0x0
	s_cmp_eq_u32 s82, 1
	s_cselect_b32 s68, 0x100, s68
	s_add_i32 s75, s84, s68
	s_mov_b32 s33, s75
	v_readlane_b32 s70, v254, 7
	v_readlane_b32 s69, v254, 10
	v_readlane_b32 s71, v254, 8
	s_cmp_ge_u32 s82, 3
	s_barrier
	s_cbranch_scc0 .LBB0_374
	s_branch .LBB0_377
